# in-proj epilogue rewritten by hand: no add of a zero bias, row pointer stepped instead of recomputed
# speedup vs baseline: 1.0209x; 1.0039x over previous
.LBB0_472:
	v_lshl_add_u32 v150, s80, 8, v142
	v_lshl_or_b32 v140, s68, 8, v144
	v_ashrrev_i32_e32 v146, 31, v150
	v_ashrrev_i32_e32 v141, 31, v140
	v_mul_lo_u32 v151, s50, v146
	v_mul_lo_u32 v148, s51, v150
	v_mad_u64_u32 v[146:147], s[68:69], s50, v150, 0
	v_lshl_add_u64 v[140:141], v[140:141], 1, s[56:57]
	v_add3_u32 v147, v147, v151, v148
	v_lshl_add_u64 v[146:147], v[146:147], 1, v[140:141]
	s_lshl_b64 s[98:99], s[50:51], 5
	v_cvt_pk_bf16_f32 v152, v126, v127
	v_cvt_pk_bf16_f32 v153, v128, v129
	v_cvt_pk_bf16_f32 v154, v122, v123
	v_cvt_pk_bf16_f32 v155, v124, v125
	flat_store_dwordx4 v[146:147], v[152:155]
	v_cvt_pk_bf16_f32 v156, v118, v119
	v_cvt_pk_bf16_f32 v157, v120, v121
	v_cvt_pk_bf16_f32 v158, v110, v111
	v_cvt_pk_bf16_f32 v159, v112, v113
	flat_store_dwordx4 v[146:147], v[156:159] offset:256
	v_lshl_add_u64 v[146:147], s[98:99], 0, v[146:147]
	v_cvt_pk_bf16_f32 v160, v114, v115
	v_cvt_pk_bf16_f32 v161, v116, v117
	v_cvt_pk_bf16_f32 v162, v106, v107
	v_cvt_pk_bf16_f32 v163, v108, v109
	flat_store_dwordx4 v[146:147], v[160:163]
	v_cvt_pk_bf16_f32 v164, v102, v103
	v_cvt_pk_bf16_f32 v165, v104, v105
	v_cvt_pk_bf16_f32 v166, v94, v95
	v_cvt_pk_bf16_f32 v167, v96, v97
	flat_store_dwordx4 v[146:147], v[164:167] offset:256
	v_lshl_add_u64 v[146:147], s[98:99], 0, v[146:147]
	v_cvt_pk_bf16_f32 v152, v98, v99
	v_cvt_pk_bf16_f32 v153, v100, v101
	v_cvt_pk_bf16_f32 v154, v90, v91
	v_cvt_pk_bf16_f32 v155, v92, v93
	flat_store_dwordx4 v[146:147], v[152:155]
	v_cvt_pk_bf16_f32 v156, v86, v87
	v_cvt_pk_bf16_f32 v157, v88, v89
	v_cvt_pk_bf16_f32 v158, v78, v79
	v_cvt_pk_bf16_f32 v159, v80, v81
	flat_store_dwordx4 v[146:147], v[156:159] offset:256
	v_lshl_add_u64 v[146:147], s[98:99], 0, v[146:147]
	v_cvt_pk_bf16_f32 v160, v82, v83
	v_cvt_pk_bf16_f32 v161, v84, v85
	v_cvt_pk_bf16_f32 v162, v74, v75
	v_cvt_pk_bf16_f32 v163, v76, v77
	flat_store_dwordx4 v[146:147], v[160:163]
	v_cvt_pk_bf16_f32 v164, v70, v71
	v_cvt_pk_bf16_f32 v165, v72, v73
	v_cvt_pk_bf16_f32 v166, v66, v67
	v_cvt_pk_bf16_f32 v167, v68, v69
	flat_store_dwordx4 v[146:147], v[164:167] offset:256
	v_lshl_add_u64 v[146:147], s[98:99], 0, v[146:147]
	v_lshl_add_u64 v[146:147], s[98:99], 2, v[146:147]
	v_cvt_pk_bf16_f32 v152, v62, v63
	v_cvt_pk_bf16_f32 v153, v64, v65
	v_cvt_pk_bf16_f32 v154, v58, v59
	v_cvt_pk_bf16_f32 v155, v60, v61
	flat_store_dwordx4 v[146:147], v[152:155]
	v_cvt_pk_bf16_f32 v156, v54, v55
	v_cvt_pk_bf16_f32 v157, v56, v57
	v_cvt_pk_bf16_f32 v158, v50, v51
	v_cvt_pk_bf16_f32 v159, v52, v53
	flat_store_dwordx4 v[146:147], v[156:159] offset:256
	v_lshl_add_u64 v[146:147], s[98:99], 0, v[146:147]
	v_cvt_pk_bf16_f32 v160, v46, v47
	v_cvt_pk_bf16_f32 v161, v48, v49
	v_cvt_pk_bf16_f32 v162, v42, v43
	v_cvt_pk_bf16_f32 v163, v44, v45
	flat_store_dwordx4 v[146:147], v[160:163]
	v_cvt_pk_bf16_f32 v164, v38, v39
	v_cvt_pk_bf16_f32 v165, v40, v41
	v_cvt_pk_bf16_f32 v166, v34, v35
	v_cvt_pk_bf16_f32 v167, v36, v37
	flat_store_dwordx4 v[146:147], v[164:167] offset:256
	v_lshl_add_u64 v[146:147], s[98:99], 0, v[146:147]
	v_cvt_pk_bf16_f32 v152, v30, v31
	v_cvt_pk_bf16_f32 v153, v32, v33
	v_cvt_pk_bf16_f32 v154, v26, v27
	v_cvt_pk_bf16_f32 v155, v28, v29
	flat_store_dwordx4 v[146:147], v[152:155]
	v_cvt_pk_bf16_f32 v156, v22, v23
	v_cvt_pk_bf16_f32 v157, v24, v25
	v_cvt_pk_bf16_f32 v158, v18, v19
	v_cvt_pk_bf16_f32 v159, v20, v21
	flat_store_dwordx4 v[146:147], v[156:159] offset:256
	v_lshl_add_u64 v[146:147], s[98:99], 0, v[146:147]
	v_cvt_pk_bf16_f32 v160, v14, v15
	v_cvt_pk_bf16_f32 v161, v16, v17
	v_cvt_pk_bf16_f32 v162, v10, v11
	v_cvt_pk_bf16_f32 v163, v12, v13
	flat_store_dwordx4 v[146:147], v[160:163]
	v_cvt_pk_bf16_f32 v164, v6, v7
	v_cvt_pk_bf16_f32 v165, v8, v9
	v_cvt_pk_bf16_f32 v166, v2, v3
	v_cvt_pk_bf16_f32 v167, v4, v5
	flat_store_dwordx4 v[146:147], v[164:167] offset:256
	s_andn2_b64 vcc, exec, s[38:39]
	s_mov_b64 s[38:39], -1
	s_mov_b64 s[98:99], s[62:63]
	s_cbranch_vccnz .LBB0_461
	s_andn2_b64 vcc, exec, s[90:91]
	s_cbranch_vccnz .LBB0_460
	s_barrier
	s_branch .LBB0_460
